# f32 input x loads (P0 row pass, P2 residual-in epilogue) marked nt
# speedup vs baseline: 1.0301x; 1.0098x over previous
.LBB0_26:
	s_ashr_i32 s31, s30, 31
	s_lshl_b64 s[6:7], s[30:31], 12
	s_add_i32 s34, s30, s42
	s_cmpk_lt_i32 s34, 0x4000
	v_lshl_add_u64 v[0:1], v[30:31], 0, s[6:7]
	s_cselect_b64 s[36:37], -1, 0
	global_load_dwordx4 v[46:49], v[0:1], off nt
	global_load_dwordx4 v[16:19], v[0:1], off offset:1024 nt
	global_load_dwordx4 v[8:11], v[0:1], off offset:2048 nt
	s_nop 0
	global_load_dwordx4 v[0:3], v[0:1], off offset:3072 nt
	s_and_b64 s[6:7], s[36:37], exec
	s_cselect_b32 s6, s34, s30
	s_ashr_i32 s7, s6, 31
	s_lshl_b64 s[6:7], s[6:7], 12
	v_lshl_add_u64 v[4:5], v[30:31], 0, s[6:7]
	global_load_dwordx4 v[24:27], v[4:5], off nt
	global_load_dwordx4 v[20:23], v[4:5], off offset:1024 nt
	global_load_dwordx4 v[12:15], v[4:5], off offset:2048 nt
	s_nop 0
	global_load_dwordx4 v[4:7], v[4:5], off offset:3072 nt
	s_lshl_b64 s[6:7], s[30:31], 11
	s_add_u32 s40, s82, s6
	s_addc_u32 s41, s83, s7
	s_ashr_i32 s35, s34, 31
	s_lshl_b64 s[6:7], s[34:35], 11
	s_add_u32 s38, s82, s6
	s_addc_u32 s39, s83, s7
	s_cmpk_gt_i32 s34, 0x3fff
	s_waitcnt vmcnt(7)
	v_mul_f32_e32 v32, v47, v47
	v_mul_f32_e32 v33, v49, v49
	s_waitcnt vmcnt(6)
	v_mul_f32_e32 v34, v17, v17
	v_mul_f32_e32 v35, v19, v19
	s_waitcnt vmcnt(5)
	v_mul_f32_e32 v42, v9, v9
	s_waitcnt lgkmcnt(0)
	v_mul_f32_e32 v43, v11, v11
	v_fmac_f32_e32 v32, v46, v46
	v_fmac_f32_e32 v33, v48, v48
	v_fmac_f32_e32 v34, v16, v16
	v_fmac_f32_e32 v35, v18, v18
	s_waitcnt vmcnt(4)
	v_mul_f32_e32 v44, v1, v1
	v_mul_f32_e32 v45, v3, v3
	v_fmac_f32_e32 v42, v8, v8
	v_fmac_f32_e32 v43, v10, v10
	v_add_f32_e32 v32, v32, v33
	v_add_f32_e32 v33, v34, v35
	v_fmac_f32_e32 v44, v0, v0
	v_fmac_f32_e32 v45, v2, v2
	v_add_f32_e32 v34, v42, v43
	v_add_f32_e32 v32, v32, v33
	v_add_f32_e32 v35, v44, v45
	v_add_f32_e32 v32, v32, v34
	v_add_f32_e32 v32, v32, v35
	s_waitcnt vmcnt(3)
	v_mul_f32_e32 v33, v25, v25
	v_mul_f32_e32 v34, v27, v27
	s_waitcnt vmcnt(2)
	v_mul_f32_e32 v35, v21, v21
	v_mul_f32_e32 v42, v23, v23
	s_waitcnt vmcnt(1)
	v_mul_f32_e32 v43, v13, v13
	v_mul_f32_e32 v44, v15, v15
	v_fmac_f32_e32 v33, v24, v24
	v_fmac_f32_e32 v34, v26, v26
	v_fmac_f32_e32 v35, v20, v20
	v_fmac_f32_e32 v42, v22, v22
	s_waitcnt vmcnt(0)
	v_mul_f32_e32 v45, v5, v5
	v_mul_f32_e32 v50, v7, v7
	v_fmac_f32_e32 v43, v12, v12
	v_fmac_f32_e32 v44, v14, v14
	v_add_f32_e32 v33, v33, v34
	v_add_f32_e32 v34, v35, v42
	v_fmac_f32_e32 v45, v4, v4
	v_fmac_f32_e32 v50, v6, v6
	v_add_f32_e32 v35, v43, v44
	v_add_f32_e32 v33, v33, v34
	v_add_f32_e32 v42, v45, v50
	v_add_f32_e32 v33, v33, v35
	v_add_f32_e32 v33, v33, v42
	ds_bpermute_b32 v51, v36, v32
	ds_bpermute_b32 v34, v36, v33
	v_cvt_pk_bf16_f32 v46, v46, v47
	v_cvt_pk_bf16_f32 v47, v48, v49
	global_store_dwordx2 v28, v[46:47], s[40:41]
	s_waitcnt lgkmcnt(1)
	v_add_f32_e32 v32, v32, v51
	s_waitcnt lgkmcnt(0)
	v_add_f32_e32 v33, v33, v34
	ds_bpermute_b32 v35, v37, v32
	ds_bpermute_b32 v34, v37, v33
	s_waitcnt lgkmcnt(1)
	v_add_f32_e32 v32, v32, v35
	s_waitcnt lgkmcnt(0)
	v_add_f32_e32 v33, v33, v34
	ds_bpermute_b32 v35, v38, v32
	ds_bpermute_b32 v34, v38, v33
	s_waitcnt lgkmcnt(1)
	v_add_f32_e32 v32, v32, v35
	s_waitcnt lgkmcnt(0)
	v_add_f32_e32 v33, v33, v34
	ds_bpermute_b32 v35, v39, v32
	ds_bpermute_b32 v34, v39, v33
	s_waitcnt lgkmcnt(1)
	v_add_f32_e32 v32, v32, v35
	s_waitcnt lgkmcnt(0)
	v_add_f32_e32 v33, v33, v34
	ds_bpermute_b32 v35, v40, v32
	ds_bpermute_b32 v34, v40, v33
	s_waitcnt lgkmcnt(1)
	v_add_f32_e32 v44, v32, v35
	s_waitcnt lgkmcnt(0)
	v_add_f32_e32 v42, v33, v34
	ds_bpermute_b32 v45, v41, v44
	ds_bpermute_b32 v43, v41, v42
	v_lshl_add_u64 v[32:33], s[40:41], 0, v[28:29]
	v_lshl_add_u64 v[34:35], s[38:39], 0, v[28:29]
	s_cbranch_scc1 .LBB0_28
	v_cvt_pk_bf16_f32 v24, v24, v25
	v_cvt_pk_bf16_f32 v25, v26, v27
	v_cvt_pk_bf16_f32 v16, v16, v17
	v_cvt_pk_bf16_f32 v17, v18, v19
	s_mov_b64 s[6:7], s[38:39]
	global_store_dwordx2 v[34:35], v[24:25], off
	global_store_dwordx2 v[32:33], v[16:17], off offset:512
	s_branch .LBB0_29

.LBB0_448:
	s_ashr_i32 s39, s38, 31
	s_lshl_b64 s[38:39], s[38:39], 8
	v_or_b32_e32 v198, s38, v186
	s_lshl_b32 s38, s60, 8
	v_add_u32_e32 v200, s38, v187
	v_readlane_b32 s40, v242, 3
	v_mov_b32_e32 v199, s39
	v_readlane_b32 s41, v242, 4
	v_ashrrev_i32_e32 v201, 31, v200
	v_lshlrev_b64 v[128:129], 12, v[200:201]
	v_lshl_add_u64 v[202:203], v[198:199], 2, s[40:41]
	v_lshl_add_u64 v[128:129], v[202:203], 0, v[128:129]
	global_load_dwordx4 v[220:223], v[128:129], off nt
	global_load_dwordx4 v[224:227], v[128:129], off offset:16 nt
	global_load_dwordx4 v[228:231], v[128:129], off offset:512 nt
	global_load_dwordx4 v[232:235], v[128:129], off offset:528 nt
	v_or_b32_e32 v208, 16, v200
	v_or_b32_e32 v206, 32, v200
	v_or_b32_e32 v204, 48, v200
	v_ashrrev_i32_e32 v209, 31, v208
	v_ashrrev_i32_e32 v207, 31, v206
	v_ashrrev_i32_e32 v205, 31, v204
	v_lshlrev_b64 v[128:129], 12, v[208:209]
	v_lshlrev_b64 v[130:131], 12, v[206:207]
	v_lshlrev_b64 v[132:133], 12, v[204:205]
	v_lshl_add_u64 v[128:129], v[202:203], 0, v[128:129]
	v_lshl_add_u64 v[130:131], v[202:203], 0, v[130:131]
	v_lshl_add_u64 v[132:133], v[202:203], 0, v[132:133]
	global_load_dwordx4 v[168:171], v[128:129], off offset:16 nt
	global_load_dwordx4 v[172:175], v[128:129], off nt
	global_load_dwordx4 v[160:163], v[128:129], off offset:528 nt
	global_load_dwordx4 v[164:167], v[128:129], off offset:512 nt
	global_load_dwordx4 v[152:155], v[130:131], off offset:16 nt
	global_load_dwordx4 v[156:159], v[130:131], off nt
	global_load_dwordx4 v[144:147], v[130:131], off offset:528 nt
	global_load_dwordx4 v[148:151], v[130:131], off offset:512 nt
	global_load_dwordx4 v[136:139], v[132:133], off offset:16 nt
	global_load_dwordx4 v[140:143], v[132:133], off nt
	s_nop 0
	global_load_dwordx4 v[128:131], v[132:133], off offset:528 nt
	s_nop 0
	global_load_dwordx4 v[132:135], v[132:133], off offset:512 nt
	v_and_b32_e32 v218, 64, v216
	v_xor_b32_e32 v217, 16, v216
	v_add_u32_e32 v218, 64, v218
	v_xor_b32_e32 v219, 32, v216
	v_cmp_lt_i32_e32 vcc, v217, v218
	v_lshlrev_b64 v[236:237], 11, v[200:201]
	v_readlane_b32 s42, v242, 5
	v_cndmask_b32_e32 v217, v216, v217, vcc
	v_cmp_lt_i32_e32 vcc, v219, v218
	v_lshlrev_b32_e32 v218, 2, v217
	v_readlane_b32 s43, v242, 6
	v_cndmask_b32_e32 v219, v216, v219, vcc
	v_lshlrev_b32_e32 v217, 2, v219
	v_readlane_b32 s44, v242, 7
	v_readlane_b32 s45, v242, 8
	v_readlane_b32 s46, v242, 9
	v_readlane_b32 s47, v242, 10
	v_readlane_b32 s48, v242, 11
	v_readlane_b32 s49, v242, 12
	v_readlane_b32 s50, v242, 13
	v_readlane_b32 s51, v242, 14
	v_readlane_b32 s52, v242, 15
	v_readlane_b32 s53, v242, 16
	v_readlane_b32 s54, v242, 17
	v_readlane_b32 s55, v242, 18
	s_waitcnt vmcnt(0)
	v_pk_fma_f32 v[126:127], v[126:127], 0.5, v[222:223] op_sel_hi:[1,0,1]
	v_pk_fma_f32 v[124:125], v[124:125], 0.5, v[220:221] op_sel_hi:[1,0,1]
	v_pk_fma_f32 v[122:123], v[122:123], 0.5, v[226:227] op_sel_hi:[1,0,1]
	v_pk_fma_f32 v[120:121], v[120:121], 0.5, v[224:225] op_sel_hi:[1,0,1]
	v_pk_fma_f32 v[118:119], v[118:119], 0.5, v[230:231] op_sel_hi:[1,0,1]
	v_pk_fma_f32 v[116:117], v[116:117], 0.5, v[228:229] op_sel_hi:[1,0,1]
	v_pk_fma_f32 v[220:221], v[114:115], 0.5, v[234:235] op_sel_hi:[1,0,1]
	v_pk_fma_f32 v[222:223], v[112:113], 0.5, v[232:233] op_sel_hi:[1,0,1]
	v_mul_f32_e32 v201, v125, v125
	v_mul_f32_e32 v219, v127, v127
	v_mul_f32_e32 v224, v121, v121
	v_mul_f32_e32 v225, v123, v123
	v_cvt_pk_bf16_f32 v114, v120, v121
	v_cvt_pk_bf16_f32 v115, v122, v123
	v_mul_f32_e32 v121, v117, v117
	v_mul_f32_e32 v123, v119, v119
	v_cvt_pk_bf16_f32 v112, v124, v125
	v_mul_f32_e32 v125, v223, v223
	v_fmac_f32_e32 v201, v124, v124
	v_fmac_f32_e32 v219, v126, v126
	v_fmac_f32_e32 v121, v116, v116
	v_fmac_f32_e32 v123, v118, v118
	v_cvt_pk_bf16_f32 v113, v126, v127
	v_mul_f32_e32 v127, v221, v221
	v_fmac_f32_e32 v224, v120, v120
	v_fmac_f32_e32 v125, v222, v222
	v_add_f32_e32 v120, v201, v219
	v_add_f32_e32 v121, v121, v123
	v_fmac_f32_e32 v225, v122, v122
	v_fmac_f32_e32 v127, v220, v220
	v_add_f32_e32 v120, v224, v120
	v_add_f32_e32 v121, v125, v121
	v_add_f32_e32 v120, v225, v120
	v_add_f32_e32 v121, v127, v121
	v_add_f32_e32 v122, v120, v121
	ds_bpermute_b32 v123, v218, v122
	v_lshl_add_u64 v[120:121], s[82:83], 0, v[236:237]
	v_lshl_add_u64 v[120:121], v[198:199], 1, v[120:121]
	global_store_dwordx4 v[120:121], v[112:115], off
	s_waitcnt lgkmcnt(0)
	s_nop 0
	v_add_f32_e32 v112, v122, v123
	ds_bpermute_b32 v113, v217, v112
	v_cvt_pk_bf16_f32 v114, v116, v117
	v_cvt_pk_bf16_f32 v115, v118, v119
	v_cvt_pk_bf16_f32 v116, v222, v223
	v_cvt_pk_bf16_f32 v117, v220, v221
	global_store_dwordx4 v[120:121], v[114:117], off offset:256
	s_and_saveexec_b64 s[40:41], s[4:5]
	s_cbranch_execz .LBB0_450
	s_waitcnt lgkmcnt(0)
	v_add_f32_e32 v112, v112, v113
	ds_write_b32 v211, v112

.LBB0_456:
	s_or_b64 exec, exec, s[40:41]
	v_add_u32_e32 v134, 0x80, v200
	v_ashrrev_i32_e32 v135, 31, v134
	s_waitcnt lgkmcnt(0)
	v_lshlrev_b64 v[64:65], 12, v[134:135]
	v_lshl_add_u64 v[64:65], v[202:203], 0, v[64:65]
	global_load_dwordx4 v[118:121], v[64:65], off nt
	global_load_dwordx4 v[122:125], v[64:65], off offset:16 nt
	global_load_dwordx4 v[126:129], v[64:65], off offset:512 nt
	global_load_dwordx4 v[130:133], v[64:65], off offset:528 nt
	v_add_u32_e32 v116, 0x90, v200
	v_add_u32_e32 v114, 0xa0, v200
	v_add_u32_e32 v112, 0xb0, v200
	v_ashrrev_i32_e32 v117, 31, v116
	v_ashrrev_i32_e32 v115, 31, v114
	v_ashrrev_i32_e32 v113, 31, v112
	v_lshlrev_b64 v[64:65], 12, v[116:117]
	v_lshlrev_b64 v[66:67], 12, v[114:115]
	v_lshlrev_b64 v[68:69], 12, v[112:113]
	v_lshl_add_u64 v[64:65], v[202:203], 0, v[64:65]
	v_lshl_add_u64 v[66:67], v[202:203], 0, v[66:67]
	v_lshl_add_u64 v[68:69], v[202:203], 0, v[68:69]
	global_load_dwordx4 v[104:107], v[64:65], off offset:16 nt
	global_load_dwordx4 v[108:111], v[64:65], off nt
	global_load_dwordx4 v[96:99], v[64:65], off offset:528 nt
	global_load_dwordx4 v[100:103], v[64:65], off offset:512 nt
	global_load_dwordx4 v[88:91], v[66:67], off offset:16 nt
	global_load_dwordx4 v[92:95], v[66:67], off nt
	global_load_dwordx4 v[80:83], v[66:67], off offset:528 nt
	global_load_dwordx4 v[84:87], v[66:67], off offset:512 nt
	global_load_dwordx4 v[72:75], v[68:69], off offset:16 nt
	global_load_dwordx4 v[76:79], v[68:69], off nt
	s_nop 0
	global_load_dwordx4 v[64:67], v[68:69], off offset:528 nt
	s_nop 0
	global_load_dwordx4 v[68:71], v[68:69], off offset:512 nt
	v_lshlrev_b64 v[134:135], 11, v[134:135]
	s_waitcnt vmcnt(15)
	v_pk_fma_f32 v[62:63], v[62:63], 0.5, v[120:121] op_sel_hi:[1,0,1]
	v_pk_fma_f32 v[60:61], v[60:61], 0.5, v[118:119] op_sel_hi:[1,0,1]
	s_waitcnt vmcnt(14)
	v_pk_fma_f32 v[58:59], v[58:59], 0.5, v[124:125] op_sel_hi:[1,0,1]
	v_pk_fma_f32 v[56:57], v[56:57], 0.5, v[122:123] op_sel_hi:[1,0,1]
	s_waitcnt vmcnt(13)
	v_pk_fma_f32 v[54:55], v[54:55], 0.5, v[128:129] op_sel_hi:[1,0,1]
	v_pk_fma_f32 v[52:53], v[52:53], 0.5, v[126:127] op_sel_hi:[1,0,1]
	s_waitcnt vmcnt(12)
	v_pk_fma_f32 v[118:119], v[50:51], 0.5, v[132:133] op_sel_hi:[1,0,1]
	v_pk_fma_f32 v[120:121], v[48:49], 0.5, v[130:131] op_sel_hi:[1,0,1]
	v_mul_f32_e32 v122, v61, v61
	v_mul_f32_e32 v123, v63, v63
	v_mul_f32_e32 v124, v57, v57
	v_mul_f32_e32 v125, v59, v59
	v_cvt_pk_bf16_f32 v50, v56, v57
	v_cvt_pk_bf16_f32 v51, v58, v59
	v_mul_f32_e32 v57, v53, v53
	v_mul_f32_e32 v59, v55, v55
	v_cvt_pk_bf16_f32 v48, v60, v61
	v_mul_f32_e32 v61, v121, v121
	v_fmac_f32_e32 v122, v60, v60
	v_fmac_f32_e32 v123, v62, v62
	v_fmac_f32_e32 v57, v52, v52
	v_fmac_f32_e32 v59, v54, v54
	v_cvt_pk_bf16_f32 v49, v62, v63
	v_mul_f32_e32 v63, v119, v119
	v_fmac_f32_e32 v124, v56, v56
	v_fmac_f32_e32 v61, v120, v120
	v_add_f32_e32 v56, v122, v123
	v_add_f32_e32 v57, v57, v59
	v_fmac_f32_e32 v125, v58, v58
	v_fmac_f32_e32 v63, v118, v118
	v_add_f32_e32 v56, v124, v56
	v_add_f32_e32 v57, v61, v57
	v_add_f32_e32 v56, v125, v56
	v_add_f32_e32 v57, v63, v57
	v_add_f32_e32 v58, v56, v57
	ds_bpermute_b32 v59, v218, v58
	v_lshl_add_u64 v[56:57], s[82:83], 0, v[134:135]
	v_lshl_add_u64 v[56:57], v[198:199], 1, v[56:57]
	global_store_dwordx4 v[56:57], v[48:51], off
	s_waitcnt lgkmcnt(0)
	s_nop 0
	v_add_f32_e32 v48, v58, v59
	ds_bpermute_b32 v49, v217, v48
	v_cvt_pk_bf16_f32 v50, v52, v53
	v_cvt_pk_bf16_f32 v51, v54, v55
	v_cvt_pk_bf16_f32 v52, v120, v121
	v_cvt_pk_bf16_f32 v53, v118, v119
	global_store_dwordx4 v[56:57], v[50:53], off offset:256
	s_and_saveexec_b64 s[40:41], s[4:5]
	s_cbranch_execz .LBB0_458
	s_waitcnt lgkmcnt(0)
	v_add_f32_e32 v48, v48, v49
	ds_write_b32 v211, v48 offset:2048
